# v48 + hand-scheduled intra-chunk scan loop (LDS ring prefetch, decay factors under MFMA chain)
# speedup vs baseline: 1.0095x; 1.0095x over previous
.LBB0_818:
	v_mov_b32_e32 v16, v155
	s_or_b32 s6, s37, s9
	v_and_b32_e32 v17, 31, v16
	v_lshrrev_b32_e32 v16, 3, v16
	s_add_i32 s6, s6, s27
	v_and_b32_e32 v16, 0x1ffffc, v16
	v_add_u32_e32 v16, s6, v16
	v_mul_lo_u32 v16, v16, s18
	v_or3_b32 v16, v16, v17, s28
	v_lshlrev_b32_e32 v16, 1, v16
	v_add_u32_e32 v17, 0x3000, v16
	v_add_u32_e32 v18, 0x6000, v16
	v_add_u32_e32 v19, 0x9000, v16
	v_add_u32_e32 v20, 0x18000, v16
	v_add_u32_e32 v21, 0x1b000, v16
	v_add_u32_e32 v22, 0x1e000, v16
	v_add_u32_e32 v23, 0x21000, v16
	global_load_ushort v175, v16, s[4:5]
	global_load_ushort v174, v17, s[4:5]
	global_load_ushort v173, v18, s[4:5]
	global_load_ushort v172, v19, s[4:5]
	global_load_ushort v171, v20, s[4:5]
	global_load_ushort v170, v21, s[4:5]
	global_load_ushort v169, v22, s[4:5]
	global_load_ushort v168, v23, s[4:5]
	v_add_u32_e32 v17, 0x30000, v16
	v_add_u32_e32 v18, 0x33000, v16
	v_add_u32_e32 v19, 0x36000, v16
	v_add_u32_e32 v20, 0x39000, v16
	v_add_u32_e32 v21, 0x48000, v16
	v_add_u32_e32 v22, 0x4b000, v16
	v_add_u32_e32 v23, 0x4e000, v16
	v_add_u32_e32 v16, 0x51000, v16
	global_load_ushort v167, v17, s[4:5]
	global_load_ushort v166, v18, s[4:5]
	global_load_ushort v165, v19, s[4:5]
	global_load_ushort v164, v20, s[4:5]
	global_load_ushort v163, v21, s[4:5]
	global_load_ushort v162, v22, s[4:5]
	global_load_ushort v146, v23, s[4:5]
	global_load_ushort v51, v16, s[4:5]
	v_mov_b32_e32 v17, v155
	v_mov_b32_e32 v16, s36
	s_waitcnt lgkmcnt(0)
	s_barrier
	ds_read_b32 v16, v16 offset:2044
	v_and_b32_e32 v32, 31, v17
	v_or_b32_e32 v176, s27, v32
	v_mul_lo_u32 v18, v176, s20
	v_ashrrev_i32_e32 v34, 5, v17
	v_lshlrev_b32_e32 v177, 4, v34
	v_add_u32_e32 v18, 0, v18
	s_mov_b32 s7, 0x15400
	v_add3_u32 v37, v18, v177, s7
	ds_read_b128 v[112:115], v37
	s_waitcnt lgkmcnt(1)
	v_pk_mul_f32 v[14:15], v[14:15], v[16:17] op_sel_hi:[1,0]
	v_pk_mul_f32 v[12:13], v[12:13], v[16:17] op_sel_hi:[1,0]
	v_pk_mul_f32 v[10:11], v[10:11], v[16:17] op_sel_hi:[1,0]
	v_pk_mul_f32 v[8:9], v[8:9], v[16:17] op_sel_hi:[1,0]
	v_pk_mul_f32 v[6:7], v[6:7], v[16:17] op_sel_hi:[1,0]
	v_pk_mul_f32 v[4:5], v[4:5], v[16:17] op_sel_hi:[1,0]
	v_pk_mul_f32 v[2:3], v[2:3], v[16:17] op_sel_hi:[1,0]
	v_pk_mul_f32 v[0:1], v[0:1], v[16:17] op_sel_hi:[1,0]
	v_or_b32_e32 v16, s23, v32
	v_lshrrev_b32_e32 v47, 1, v17
	v_mul_lo_u32 v16, v16, s20
	v_add_u32_e32 v207, 0, v16
	v_xor_b32_e32 v16, v34, v47
	v_or_b32_e32 v33, s22, v32
	v_lshlrev_b32_e32 v16, 4, v16
	v_mad_u32_u24 v35, v33, s20, 0
	s_mov_b32 s7, 0x1dc00
	v_lshlrev_b32_e32 v36, 3, v34
	v_and_b32_e32 v16, 0xf0, v16
	v_add3_u32 v46, v35, v177, s7
	v_add_u32_e32 v210, v35, v16
	v_bitop3_b32 v16, v36, v32, s23 bitop3:0x1e
	ds_read_b128 v[116:119], v37 offset:32
	v_lshlrev_b32_e32 v20, 1, v16
	ds_read_b128 v[16:19], v46
	v_and_b32_e32 v20, 0xf0, v20
	v_add_u32_e32 v42, v207, v20
	s_waitcnt lgkmcnt(0)
	v_mfma_f32_32x32x16_bf16 v[16:31], v[112:115], v[16:19], 0
	ds_read_b128 v[38:41], v46 offset:32
	ds_read_b128 v[120:123], v37 offset:224
	v_add_u32_e32 v124, 16, v36
	v_lshrrev_b32_e32 v43, 3, v124
	v_xor_b32_e32 v43, v43, v47
	v_lshlrev_b32_e32 v43, 4, v43
	v_and_b32_e32 v43, 0xf0, v43
	v_bitop3_b32 v124, v124, v32, s23 bitop3:0x1e
	s_waitcnt lgkmcnt(1)
	v_mfma_f32_32x32x16_bf16 v[16:31], v[116:119], v[38:41], v[16:31]
	v_add_u32_e32 v125, v35, v43
	v_lshlrev_b32_e32 v124, 1, v124
	ds_read_b128 v[42:45], v42 offset:52224
	ds_read_b128 v[178:181], v125
	v_and_b32_e32 v132, 0xf0, v124
	ds_read_b128 v[124:127], v37 offset:64
	ds_read_b128 v[128:131], v46 offset:64
	v_add_u32_e32 v38, v207, v132
	v_add_u32_e32 v132, 32, v36
	v_lshrrev_b32_e32 v39, 3, v132
	v_xor_b32_e32 v39, v39, v47
	s_waitcnt lgkmcnt(0)
	v_mfma_f32_32x32x16_bf16 v[16:31], v[124:127], v[128:131], v[16:31]
	v_lshlrev_b32_e32 v39, 4, v39
	v_and_b32_e32 v39, 0xf0, v39
	v_add_u32_e32 v133, v35, v39
	ds_read_b128 v[128:131], v37 offset:96
	ds_read_b128 v[38:41], v38 offset:52224
	ds_read_b128 v[182:185], v133
	ds_read_b128 v[136:139], v46 offset:96
	v_bitop3_b32 v132, v132, v32, s23 bitop3:0x1e
	v_lshlrev_b32_e32 v132, 1, v132
	s_waitcnt lgkmcnt(0)
	v_mfma_f32_32x32x16_bf16 v[16:31], v[128:131], v[136:139], v[16:31]
	v_and_b32_e32 v186, 0xf0, v132
	ds_read_b128 v[132:135], v37 offset:128
	ds_read_b128 v[140:143], v46 offset:128
	v_add_u32_e32 v198, 48, v36
	v_lshrrev_b32_e32 v136, 3, v198
	v_xor_b32_e32 v136, v136, v47
	v_lshlrev_b32_e32 v136, 4, v136
	v_add_u32_e32 v190, v207, v186
	v_and_b32_e32 v186, 0xf0, v136
	ds_read_b128 v[136:139], v37 offset:160
	s_waitcnt lgkmcnt(1)
	v_mfma_f32_32x32x16_bf16 v[16:31], v[132:135], v[140:143], v[16:31]
	v_add_u32_e32 v140, v35, v186
	ds_read_b128 v[186:189], v46 offset:160
	ds_read_b128 v[190:193], v190 offset:52224
	ds_read_b128 v[194:197], v140
	v_bitop3_b32 v211, v198, v32, s23 bitop3:0x1e
	ds_read_b128 v[140:143], v37 offset:192
	ds_read_b128 v[198:201], v46 offset:192
	v_add_u32_e32 v218, 64, v36
	v_lshlrev_b32_e32 v37, 1, v211
	v_and_b32_e32 v37, 0xf0, v37
	s_waitcnt lgkmcnt(4)
	v_mfma_f32_32x32x16_bf16 v[16:31], v[136:139], v[186:189], v[16:31]
	v_lshrrev_b32_e32 v186, 3, v218
	v_xor_b32_e32 v186, v186, v47
	v_lshlrev_b32_e32 v186, 4, v186
	v_and_b32_e32 v211, 0xf0, v186
	v_add_u32_e32 v37, v207, v37
	s_lshl_b32 s7, s27, 2
	s_add_i32 s7, s36, s7
	s_waitcnt lgkmcnt(0)
	v_mfma_f32_32x32x16_bf16 v[16:31], v[140:143], v[198:201], v[16:31]
	ds_read_b128 v[186:189], v210
	ds_read_b128 v[198:201], v46 offset:224
	v_add_u32_e32 v46, v35, v211
	ds_read_b128 v[210:213], v37 offset:52224
	ds_read_b128 v[214:217], v46
	v_add_u32_e32 v46, 0x50, v36
	v_bitop3_b32 v37, v218, v32, s23 bitop3:0x1e
	v_lshlrev_b32_e32 v37, 1, v37
	v_and_b32_e32 v37, 0xf0, v37
	s_waitcnt lgkmcnt(3)
	v_mfma_f32_32x32x16_bf16 v[0:15], v[186:189], v[42:45], v[0:15]
	v_add_u32_e32 v37, v207, v37
	s_andn2_b64 vcc, exec, s[50:51]
	v_mfma_f32_32x32x16_bf16 v[0:15], v[178:181], v[38:41], v[0:15]
	v_mfma_f32_32x32x16_bf16 v[0:15], v[182:185], v[190:193], v[0:15]
	s_waitcnt lgkmcnt(2)
	v_mfma_f32_32x32x16_bf16 v[16:31], v[120:123], v[198:201], v[16:31]
	v_lshrrev_b32_e32 v198, 3, v46
	v_xor_b32_e32 v198, v198, v47
	v_lshlrev_b32_e32 v198, 4, v198
	v_and_b32_e32 v42, 0xf0, v198
	v_add_u32_e32 v186, v35, v42
	ds_read_b128 v[42:45], v37 offset:52224
	ds_read_b128 v[186:189], v186
	v_bitop3_b32 v37, v46, v32, s23 bitop3:0x1e
	s_waitcnt lgkmcnt(3)
	v_mfma_f32_32x32x16_bf16 v[0:15], v[194:197], v[210:213], v[0:15]
	v_add_u32_e32 v46, 0x60, v36
	v_lshrrev_b32_e32 v38, 3, v46
	v_xor_b32_e32 v38, v38, v47
	v_lshlrev_b32_e32 v37, 1, v37
	v_lshlrev_b32_e32 v38, 4, v38
	v_and_b32_e32 v37, 0xf0, v37
	v_and_b32_e32 v38, 0xf0, v38
	s_waitcnt lgkmcnt(1)
	v_mfma_f32_32x32x16_bf16 v[0:15], v[214:217], v[42:45], v[0:15]
	v_add_u32_e32 v37, v207, v37
	v_add_u32_e32 v178, v35, v38
	ds_read_b128 v[38:41], v37 offset:52224
	ds_read_b128 v[178:181], v178
	v_bitop3_b32 v37, v46, v32, s23 bitop3:0x1e
	v_add_u32_e32 v46, 0x70, v36
	v_lshrrev_b32_e32 v182, 3, v46
	v_lshlrev_b32_e32 v37, 1, v37
	s_waitcnt lgkmcnt(1)
	v_mfma_f32_32x32x16_bf16 v[0:15], v[186:189], v[38:41], v[0:15]
	v_xor_b32_e32 v47, v182, v47
	v_and_b32_e32 v37, 0xf0, v37
	v_lshlrev_b32_e32 v47, 4, v47
	v_add_u32_e32 v37, v207, v37
	v_and_b32_e32 v47, 0xf0, v47
	v_add_u32_e32 v47, v35, v47
	ds_read_b128 v[182:185], v37 offset:52224
	ds_read_b128 v[190:193], v47
	s_waitcnt lgkmcnt(1)
	v_mfma_f32_32x32x16_bf16 v[0:15], v[178:181], v[182:185], v[0:15]
	v_bitop3_b32 v37, v46, v32, s23 bitop3:0x1e
	v_lshlrev_b32_e32 v37, 1, v37
	v_and_b32_e32 v37, 0xf0, v37
	v_add_u32_e32 v46, s7, v177
	v_add_u32_e32 v37, v207, v37
	ds_read_b128 v[42:45], v46 offset:1632
	ds_read_b128 v[38:41], v46 offset:1568
	ds_read_b128 v[186:189], v46 offset:1600
	ds_read_b128 v[194:197], v37 offset:52224
	ds_read_b128 v[198:201], v46 offset:1536
	s_waitcnt lgkmcnt(1)
	v_mfma_f32_32x32x16_bf16 v[0:15], v[190:193], v[194:197], v[0:15]
	v_mul_f32_e64 v30, v30, v44
	v_mul_f32_e64 v31, v31, v45
	v_mul_f32_e64 v28, v28, v42
	v_mul_f32_e64 v29, v29, v43
	v_mul_f32_e64 v26, v26, v188
	v_mul_f32_e64 v27, v27, v189
	v_pk_mul_f32 v[24:25], v[24:25], v[186:187]
	v_pk_mul_f32 v[22:23], v[22:23], v[40:41]
	v_pk_mul_f32 v[20:21], v[20:21], v[38:39]
	s_waitcnt lgkmcnt(0)
	v_pk_mul_f32 v[18:19], v[18:19], v[200:201]
	v_pk_mul_f32 v[16:17], v[16:17], v[198:199]
	s_cbranch_vccnz .LBB0_821
	v_lshl_add_u32 v37, v176, 2, s36
	ds_read_b32 v178, v37
	v_cndmask_b32_e64 v37, 0, 1, s[52:53]
	v_lshrrev_b32_e32 v181, 1, v33
	v_and_b32_e32 v33, 8, v36
	s_add_i32 s7, 0, 0x4400
	v_lshlrev_b32_e32 v37, 11, v37
	v_add_u32_e32 v182, v35, v33
	v_mov_b32_e32 v33, s7
	v_add_u32_e32 v179, 0, v37
	v_lshlrev_b32_e32 v180, 2, v34
	v_mad_u32_u24 v183, v32, s20, v33
	s_mov_b32 s7, s34
	v_add_u32_e32 v183, v183, v177
	v_add_u32_e32 v179, v179, v177
	v_add_u32_e32 v179, 0x22000, v179
	ds_read_b128 v[96:99], v183 offset:0
	ds_read_b128 v[100:103], v183 offset:32
	ds_read_b128 v[104:107], v183 offset:64
	ds_read_b128 v[108:111], v183 offset:96
.LBB0_820:
	ds_read_b128 v[246:249], v179 offset:0
	ds_read_b128 v[184:187], v179 offset:512
	ds_read_b64 v[196:197], v179 offset:32
	ds_read_b64 v[250:251], v179 offset:40
	ds_read_b128 v[188:191], v179 offset:544
	v_lshrrev_b32_e32 v177, 3, v180
	s_waitcnt lgkmcnt(8)
	v_mfma_f32_32x32x16_bf16 v[32:47], v[96:99], v[112:115], 0
	ds_read_b128 v[96:99], v183 offset:128
	v_cmp_le_i32_e32 vcc, v180, v176
	s_waitcnt lgkmcnt(5)
	v_sub_f32_e32 v246, v178, v246
	v_mul_f32_e32 v246, 0x3fb8aa3b, v246
	v_cndmask_b32_e32 v246, v239, v246, vcc
	v_exp_f32_e32 v246, v246
	v_add_u32_e32 v241, 1, v180
	v_mfma_f32_32x32x16_bf16 v[32:47], v[100:103], v[116:119], v[32:47]
	ds_read_b128 v[100:103], v183 offset:160
	v_cmp_le_i32_e32 vcc, v241, v176
	s_waitcnt lgkmcnt(5)
	v_mul_f32_e32 v184, v184, v246
	v_sub_f32_e32 v247, v178, v247
	v_mul_f32_e32 v247, 0x3fb8aa3b, v247
	v_cndmask_b32_e32 v247, v239, v247, vcc
	v_exp_f32_e32 v247, v247
	v_mfma_f32_32x32x16_bf16 v[32:47], v[104:107], v[124:127], v[32:47]
	ds_read_b128 v[104:107], v183 offset:192
	v_add_u32_e32 v241, 2, v180
	v_cmp_le_i32_e32 vcc, v241, v176
	v_mul_f32_e32 v185, v185, v247
	v_sub_f32_e32 v248, v178, v248
	v_mul_f32_e32 v248, 0x3fb8aa3b, v248
	v_cndmask_b32_e32 v248, v239, v248, vcc
	v_mfma_f32_32x32x16_bf16 v[32:47], v[108:111], v[128:131], v[32:47]
	ds_read_b128 v[108:111], v183 offset:224
	v_exp_f32_e32 v248, v248
	v_add_u32_e32 v241, 3, v180
	v_cmp_le_i32_e32 vcc, v241, v176
	v_mul_f32_e32 v186, v186, v248
	v_sub_f32_e32 v249, v178, v249
	v_mul_f32_e32 v249, 0x3fb8aa3b, v249
	s_waitcnt lgkmcnt(3)
	v_mfma_f32_32x32x16_bf16 v[32:47], v[96:99], v[132:135], v[32:47]
	v_xor_b32_e32 v96, v177, v181
	v_and_b32_e32 v96, 15, v96
	v_lshl_add_u32 v96, v96, 4, v182
	v_add_u32_e32 v98, 1, v177
	v_xor_b32_e32 v98, v98, v181
	v_and_b32_e32 v98, 15, v98
	v_lshl_add_u32 v98, v98, 4, v182
	ds_read_b64 v[96:97], v96
	ds_read_b64 v[98:99], v98
	v_cndmask_b32_e32 v249, v239, v249, vcc
	v_exp_f32_e32 v249, v249
	v_add_u32_e32 v241, 8, v180
	v_cmp_le_i32_e32 vcc, v241, v176
	v_mul_f32_e32 v187, v187, v249
	ds_read_b128 v[246:249], v179 offset:64
	ds_read_b128 v[192:195], v179 offset:576
	v_sub_f32_e32 v196, v178, v196
	s_waitcnt lgkmcnt(6)
	v_mfma_f32_32x32x16_bf16 v[32:47], v[100:103], v[136:139], v[32:47]
	v_add_u32_e32 v100, 2, v177
	v_xor_b32_e32 v100, v100, v181
	v_and_b32_e32 v100, 15, v100
	v_lshl_add_u32 v100, v100, 4, v182
	v_add_u32_e32 v102, 3, v177
	v_xor_b32_e32 v102, v102, v181
	v_and_b32_e32 v102, 15, v102
	v_lshl_add_u32 v102, v102, 4, v182
	ds_read_b64 v[100:101], v100
	ds_read_b64 v[102:103], v102
	v_mul_f32_e32 v196, 0x3fb8aa3b, v196
	v_cndmask_b32_e32 v196, v239, v196, vcc
	v_exp_f32_e32 v196, v196
	v_add_u32_e32 v241, 9, v180
	v_cmp_le_i32_e32 vcc, v241, v176
	v_mul_f32_e32 v188, v188, v196
	s_waitcnt lgkmcnt(7)
	v_mfma_f32_32x32x16_bf16 v[32:47], v[104:107], v[140:143], v[32:47]
	v_sub_f32_e32 v197, v178, v197
	v_mul_f32_e32 v197, 0x3fb8aa3b, v197
	v_cndmask_b32_e32 v197, v239, v197, vcc
	v_exp_f32_e32 v197, v197
	v_add_u32_e32 v241, 10, v180
	v_cmp_le_i32_e32 vcc, v241, v176
	s_waitcnt lgkmcnt(6)
	v_mfma_f32_32x32x16_bf16 v[32:47], v[108:111], v[120:123], v[32:47]
	v_mul_f32_e32 v189, v189, v197
	v_sub_f32_e32 v250, v178, v250
	v_mul_f32_e32 v250, 0x3fb8aa3b, v250
	v_cndmask_b32_e32 v250, v239, v250, vcc
	v_exp_f32_e32 v250, v250
	v_add_u32_e32 v241, 11, v180
	v_cmp_le_i32_e32 vcc, v241, v176
	v_mul_f32_e32 v190, v190, v250
	v_sub_f32_e32 v251, v178, v251
	v_mul_f32_e32 v251, 0x3fb8aa3b, v251
	v_cndmask_b32_e32 v251, v239, v251, vcc
	v_exp_f32_e32 v251, v251
	v_add_u32_e32 v241, 16, v180
	v_cmp_le_i32_e32 vcc, v241, v176
	v_mul_f32_e32 v191, v191, v251
	ds_read_b64 v[196:197], v179 offset:96
	ds_read_b64 v[250:251], v179 offset:104
	ds_read_b128 v[242:245], v179 offset:608
	s_waitcnt lgkmcnt(6)
	v_sub_f32_e32 v246, v178, v246
	v_mul_f32_e32 v246, 0x3fb8aa3b, v246
	v_cndmask_b32_e32 v246, v239, v246, vcc
	v_exp_f32_e32 v246, v246
	v_add_u32_e32 v241, 17, v180
	v_cmp_le_i32_e32 vcc, v241, v176
	s_waitcnt lgkmcnt(5)
	v_mul_f32_e32 v192, v192, v246
	v_sub_f32_e32 v247, v178, v247
	v_mul_f32_e32 v247, 0x3fb8aa3b, v247
	v_cndmask_b32_e32 v247, v239, v247, vcc
	v_exp_f32_e32 v247, v247
	v_add_u32_e32 v241, 18, v180
	v_cmp_le_i32_e32 vcc, v241, v176
	v_mul_f32_e32 v193, v193, v247
	v_sub_f32_e32 v248, v178, v248
	v_mul_f32_e32 v248, 0x3fb8aa3b, v248
	v_cndmask_b32_e32 v248, v239, v248, vcc
	v_exp_f32_e32 v248, v248
	v_add_u32_e32 v241, 19, v180
	v_cmp_le_i32_e32 vcc, v241, v176
	v_mul_f32_e32 v194, v194, v248
	v_sub_f32_e32 v249, v178, v249
	v_mul_f32_e32 v249, 0x3fb8aa3b, v249
	v_cndmask_b32_e32 v249, v239, v249, vcc
	v_exp_f32_e32 v249, v249
	v_add_u32_e32 v241, 24, v180
	v_cmp_le_i32_e32 vcc, v241, v176
	v_mul_f32_e32 v195, v195, v249
	s_waitcnt lgkmcnt(1)
	v_sub_f32_e32 v196, v178, v196
	v_mul_f32_e32 v196, 0x3fb8aa3b, v196
	v_cndmask_b32_e32 v196, v239, v196, vcc
	v_exp_f32_e32 v196, v196
	v_add_u32_e32 v241, 25, v180
	v_cmp_le_i32_e32 vcc, v241, v176
	s_waitcnt lgkmcnt(0)
	v_mul_f32_e32 v242, v242, v196
	v_sub_f32_e32 v197, v178, v197
	v_mul_f32_e32 v197, 0x3fb8aa3b, v197
	v_cndmask_b32_e32 v197, v239, v197, vcc
	v_exp_f32_e32 v197, v197
	v_add_u32_e32 v241, 26, v180
	v_cmp_le_i32_e32 vcc, v241, v176
	v_mul_f32_e32 v243, v243, v197
	v_sub_f32_e32 v250, v178, v250
	v_mul_f32_e32 v250, 0x3fb8aa3b, v250
	v_cndmask_b32_e32 v250, v239, v250, vcc
	v_exp_f32_e32 v250, v250
	v_add_u32_e32 v241, 27, v180
	v_cmp_le_i32_e32 vcc, v241, v176
	v_mul_f32_e32 v244, v244, v250
	v_sub_f32_e32 v251, v178, v251
	v_mul_f32_e32 v251, 0x3fb8aa3b, v251
	v_cndmask_b32_e32 v251, v239, v251, vcc
	v_exp_f32_e32 v251, v251
	s_nop 0
	v_mul_f32_e32 v245, v245, v251
	v_mul_f32_e32 v32, v32, v184
	v_mul_f32_e32 v33, v33, v185
	v_mul_f32_e32 v34, v34, v186
	v_mul_f32_e32 v35, v35, v187
	v_mul_f32_e32 v36, v36, v188
	v_mul_f32_e32 v37, v37, v189
	v_mul_f32_e32 v38, v38, v190
	v_mul_f32_e32 v39, v39, v191
	v_mul_f32_e32 v40, v40, v192
	v_mul_f32_e32 v41, v41, v193
	v_mul_f32_e32 v42, v42, v194
	v_mul_f32_e32 v43, v43, v195
	v_mul_f32_e32 v44, v44, v242
	v_mul_f32_e32 v45, v45, v243
	v_mul_f32_e32 v46, v46, v244
	v_mul_f32_e32 v47, v47, v245
	v_cvt_pk_bf16_f32 v32, v32, v33
	v_cvt_pk_bf16_f32 v33, v34, v35
	v_cvt_pk_bf16_f32 v34, v36, v37
	v_cvt_pk_bf16_f32 v35, v38, v39
	v_cvt_pk_bf16_f32 v36, v40, v41
	v_cvt_pk_bf16_f32 v37, v42, v43
	v_cvt_pk_bf16_f32 v38, v44, v45
	v_cvt_pk_bf16_f32 v39, v46, v47
	v_add_u32_e32 v183, 0x2200, v183
	v_add_u32_e32 v179, 0x80, v179
	v_mfma_f32_32x32x16_bf16 v[16:31], v[32:35], v[96:99], v[16:31]
	v_add_u32_e32 v180, 32, v180
	s_add_i32 s7, s7, -1
	v_mfma_f32_32x32x16_bf16 v[16:31], v[36:39], v[100:103], v[16:31]
	ds_read_b128 v[96:99], v183 offset:0
	ds_read_b128 v[100:103], v183 offset:32
	ds_read_b128 v[104:107], v183 offset:64
	ds_read_b128 v[108:111], v183 offset:96
	s_cmp_lg_u32 s7, 0
	s_cbranch_scc1 .LBB0_820
	s_waitcnt lgkmcnt(0)
